# sample-sequence conv group: plus a per-block near prefetch of the next state rows into the CU's L1/L2 (row loads no longer pay a full round trip each)
# speedup vs baseline: 1.0576x; 1.0263x over previous
.LBB0_519:
	s_cmp_lt_u32 s35, 19
	s_cbranch_scc0 .Lsconv_l1_skip
	s_add_u32 s98, s4, 0x3000
	s_addc_u32 s99, s5, 0
	global_load_dword v252, v249, s[98:99]
	s_cmp_lt_u32 s35, 13
	s_cbranch_scc0 .Lsconv_l1_skip
	s_add_u32 s98, s98, 0x2000
	s_addc_u32 s99, s99, 0
	global_load_dword v252, v249, s[98:99]
